# P0 weight-transpose loop: no longer waits for the previous tile's store acknowledgement at the loop top
# baseline (speedup 1.0000x reference)
; __device__ __forceinline__ void xpose_lds(const float (&v)[8], float* scr, int tid) {
; #pragma unroll
;     for (int i = 0; i < 8; ++i) scr[((tid >> 6) + 8 * i) * 65 + (tid & 63)] = v[i];
; }
; __device__ __forceinline__ void xpose_write(const XDesc& d, int tile, const float* scr, int tid) {
;     const int ntn = d.Npad / 64, kb = tile / ntn, nb = tile % ntn, k0 = kb * 64, n0 = nb * 64;
;     const int nl = tid >> 3, kc = (tid & 7) * 8, n = n0 + nl;
;     const int orow = d.rowoff + (d.mode == 1 ? ((n % DFF) * 2 + n / DFF) : n);
;     const float* s = scr + kc * 65 + nl;
; __device__ __forceinline__ void p0_prep(const Args& a, unsigned char* lds, int tid) {
;     ...
;     unsigned char* ws = a.ws;
;     float* scr = (float*)lds;
;     float* cs = (float*)(lds + 16640);
;     float* red = (float*)(lds + 16640 + 32768);
;     const int G = gridDim.x, bid = blockIdx.x;
;     if (bid == 0) { unsigned* bw = (unsigned*)(ws + WS_BAR); for (int i = tid; i < 3456; i += NTHREADS) bw[i] = 0u; }
;     constexpr int T_GU = 16 * 88, T_DN = 44 * 16, T_DIN = 16 * 36, T_SQ = 16 * 16, T_L64 = 16 * 1, T_G1 = 16 * 6;
;     constexpr int NDESC = 4 + 4 + 1 + 1 + 6 + 2 + 2 + 2 + 1;
;     int total = 4 * T_GU + 4 * T_DN + T_DIN + T_SQ + 6 * T_SQ + 4 * T_L64 + 2 * T_G1 + T_SQ;
;     {
;         XDesc d, dn; int r = 0, rn = 0; float v[8], vn[8];
;         int it = bid;
;         if (it < total) { P0_DECODE(it, d, r); xpose_load(d, r, tid, v); }
.LBB0_58:
	s_add_u32 s0, s16, 0x3300000
	s_addc_u32 s1, s17, 0
	v_writelane_b32 v248, s0, 46
	v_ashrrev_i32_e32 v1, 6, v18
	v_and_b32_e32 v84, 63, v18
	v_writelane_b32 v248, s1, 47
	s_add_u32 s0, s16, 0x2200000
	s_addc_u32 s1, s17, 0
	v_writelane_b32 v248, s0, 48
	s_nop 1
	v_writelane_b32 v248, s1, 49
	s_add_u32 s0, s16, 0x5b00000
	s_addc_u32 s1, s17, 0
	v_writelane_b32 v248, s0, 50
	s_add_u32 s6, s16, 0x5600000
	s_addc_u32 s7, s17, 0
	v_writelane_b32 v248, s1, 51
	s_andn2_b64 vcc, exec, s[14:15]
	s_cbranch_vccnz .LBB0_124
	v_lshlrev_b32_e32 v10, 3, v18
	s_movk_i32 s0, 0x104
	v_ashrrev_i32_e32 v19, 3, v18
	v_and_b32_e32 v20, 56, v10
	v_lshl_add_u32 v23, v84, 2, 0
	v_mul_lo_u32 v24, v1, s0
	v_mul_u32_u24_e32 v10, 0x104, v20
	v_lshlrev_b32_e32 v11, 2, v19
	v_mov_b32_e32 v21, 0
	s_mov_b32 s15, 0
	v_add3_u32 v22, 0, v10, v11
	v_mov_b32_e32 v10, v21
	v_mov_b32_e32 v11, v21
	v_mov_b32_e32 v12, v21
	v_mov_b32_e32 v13, v21
	v_mov_b32_e32 v14, v21
	v_mov_b32_e32 v15, v21
	v_mov_b32_e32 v16, v21
	v_mov_b32_e32 v17, v21
	v_add_u32_e32 v23, v23, v24
	v_lshlrev_b32_e32 v20, 1, v20
	s_mov_b32 s34, 0
	s_mov_b32 s33, s68
	s_waitcnt vmcnt(0)
	s_branch .LBB0_61

; __device__ __forceinline__ void p0_prep(const Args& a, unsigned char* lds, int tid) {
;     ...
;         while (it < total) {
;             xpose_lds(v, scr, tid);
;             __syncthreads();
;             const int itn = it + G;
;             if (itn < total) { P0_DECODE(itn, dn, rn); xpose_load(dn, rn, tid, vn); }
;             xpose_write(d, r, scr, tid);
;             __syncthreads();
;             d = dn; r = rn; it = itn;
.LBB0_61:
	s_add_i32 s33, s33, s18
	s_cmpk_gt_i32 s33, 0x2c3f
	ds_write_b32 v23, v2
	ds_write_b32 v23, v3 offset:2080
	ds_write_b32 v23, v4 offset:4160
	ds_write_b32 v23, v5 offset:6240
	ds_write_b32 v23, v6 offset:8320
	ds_write_b32 v23, v7 offset:10400
	ds_write_b32 v23, v8 offset:12480
	ds_write_b32 v23, v9 offset:14560
	s_cselect_b64 s[20:21], -1, 0
	v_mov_b64_e32 v[2:3], v[10:11]
	s_and_b64 vcc, exec, s[20:21]
	v_mov_b64_e32 v[4:5], v[12:13]
	v_mov_b64_e32 v[6:7], v[14:15]
	v_mov_b64_e32 v[8:9], v[16:17]
	s_waitcnt lgkmcnt(0)
	s_barrier
	s_cbranch_vccnz .LBB0_120
	s_cmpk_gt_i32 s33, 0x15ff
	s_mov_b64 s[0:1], -1
	s_cbranch_scc0 .LBB0_86
	s_cmpk_gt_u32 s33, 0x20ff
	s_cbranch_scc0 .LBB0_83
	s_cmpk_gt_u32 s33, 0x233f
	s_cbranch_scc0 .LBB0_77
	s_cmpk_gt_u32 s33, 0x243f
	s_cbranch_scc0 .LBB0_78
	s_cmpk_gt_u32 s33, 0x2a3f
	s_cbranch_scc0 .LBB0_74
	s_cmpk_gt_u32 s33, 0x2a7f
	s_cbranch_scc0 .LBB0_71
	s_cmpk_gt_u32 s33, 0x2b3f
	s_cbranch_scc0 .LBB0_122
	v_readlane_b32 s36, v248, 0
	v_readlane_b32 s40, v248, 4
	v_readlane_b32 s41, v248, 5
	s_add_i32 s34, s33, 0xffffd4c0
	v_readlane_b32 s37, v248, 1
	v_readlane_b32 s38, v248, 2
	v_readlane_b32 s39, v248, 3
	v_readlane_b32 s42, v248, 6
	v_readlane_b32 s43, v248, 7
	s_mov_b64 s[2:3], s[40:41]
	s_mov_b64 s[0:1], 0
	s_cbranch_execz .LBB0_123
